# grid barrier: L1/L2 invalidate (buffer_inv sc1) issued before the spin (non-leaders) / right after the release write-back (XCD leader) instead of after the flag; no loads occur on the CU in between
# speedup vs baseline: 1.0874x; 1.0146x over previous
.LBB0_800:
	s_or_b64 exec, exec, s[10:11]
	v_cvt_f32_u32_e32 v4, v2
	s_waitcnt vmcnt(0)
	v_readfirstlane_b32 s8, v3
	v_sub_u32_e32 v3, 0, v2
	v_rcp_iflag_f32_e32 v4, v4
	v_add_u32_e32 v5, s8, v1
	v_mul_f32_e32 v4, 0x4f7ffffe, v4
	v_cvt_u32_f32_e32 v4, v4
	v_mul_lo_u32 v1, v3, v4
	v_mul_hi_u32 v1, v4, v1
	v_add_u32_e32 v1, v4, v1
	v_mul_hi_u32 v1, v5, v1
	v_mul_lo_u32 v3, v1, v2
	v_sub_u32_e32 v3, v5, v3
	v_add_u32_e32 v4, 1, v1
	v_cmp_ge_u32_e32 vcc, v3, v2
	s_nop 1
	v_cndmask_b32_e32 v1, v1, v4, vcc
	v_sub_u32_e32 v4, v3, v2
	v_cndmask_b32_e32 v3, v3, v4, vcc
	v_add_u32_e32 v4, 1, v1
	v_cmp_ge_u32_e32 vcc, v3, v2
	v_add_u32_e32 v3, 1, v5
	s_nop 0
	v_cndmask_b32_e32 v1, v1, v4, vcc
	v_mul_lo_u32 v4, v2, v1
	v_add_u32_e32 v2, v4, v2
	v_cmp_ne_u32_e32 vcc, v3, v2
	s_and_saveexec_b64 s[8:9], vcc
	s_xor_b64 s[8:9], exec, s[8:9]
	s_cbranch_execz .LBB0_814
	s_waitcnt lgkmcnt(0)
	buffer_inv sc1
	global_load_dword v0, v163, s[6:7] offset:1024 sc1
	s_add_u32 s12, s6, 0x2400
	s_addc_u32 s13, s7, 0
	s_waitcnt vmcnt(0)
	v_cmp_eq_u32_e32 vcc, v0, v1
	s_and_saveexec_b64 s[10:11], vcc
	s_cbranch_execz .LBB0_813
	s_mov_b32 s24, 1
	s_mov_b64 s[14:15], 0
	s_branch .LBB0_804

.LBB0_813:
	s_or_b64 exec, exec, s[10:11]
	s_waitcnt vmcnt(0)
	s_waitcnt vmcnt(0)

.LBB0_815:
	s_mov_b64 s[8:9], exec
	buffer_wbl2 sc1
	s_waitcnt lgkmcnt(0)
	s_waitcnt vmcnt(0)
	buffer_inv sc1
	v_mbcnt_lo_u32_b32 v1, s8, 0
	v_mbcnt_hi_u32_b32 v1, s9, v1
	v_cmp_eq_u32_e32 vcc, 0, v1
	s_and_saveexec_b64 s[10:11], vcc
	s_cbranch_execz .LBB0_817
	s_bcnt1_i32_b64 s8, s[8:9]
	v_mov_b32_e32 v2, s8
	v_mov_b32_e32 v3, 0x3000
	global_atomic_add v2, v3, v2, s[4:5] offset:1024 sc0

.LBB0_833:
	s_or_b64 exec, exec, s[4:5]
	s_mov_b64 s[4:5], exec
	v_mbcnt_lo_u32_b32 v0, s4, 0
	v_mbcnt_hi_u32_b32 v0, s5, v0
	v_cmp_eq_u32_e32 vcc, 0, v0
	s_waitcnt vmcnt(0)
	s_and_saveexec_b64 s[8:9], vcc
	s_cbranch_execnz .LBB0_834
	s_getpc_b64 s[98:99]
